# v39 + LoRA stage-1 GEMM tiles (ldo 1280) branch around the bj=1 MFMA blocks: B columns 128-255 of each LoRA group are zero rows by this kernel's padding
# baseline (speedup 1.0000x reference)
; #define LDA(dst, b, h) _Pragma("unroll") for (int m = 0; m < 4; ++m) _Pragma("unroll") for (int k = 0; k < 2; ++k) \
;     dst[m][k] = *reinterpret_cast<const bf16x8*>((char*)SA(b, h) + lds_byte(wr * 64 + m * 16 + fr, k * 32 + fq * 8))
; #define LDB(dst, b, h) _Pragma("unroll") for (int n = 0; n < 2; ++n) _Pragma("unroll") for (int k = 0; k < 2; ++k) \
;     dst[n][k] = *reinterpret_cast<const bf16x8*>((char*)SB(b, h) + lds_byte(wc * 32 + n * 16 + fr, k * 32 + fq * 8))
; #define MMA(ai, bj, At_, Bt_) do { __builtin_amdgcn_s_setprio(1); \
;     _Pragma("unroll") for (int m = 0; m < 4; ++m) _Pragma("unroll") for (int n = 0; n < 2; ++n) _Pragma("unroll") for (int k = 0; k < 2; ++k) \
;       acc[ai][bj][m][n] = __builtin_amdgcn_mfma_f32_16x16x32_bf16(Bt_[n][k], At_[m][k], acc[ai][bj][m][n], 0, 0, 0); \
;     __builtin_amdgcn_s_setprio(0); } while (0)
; #define WAIT_V(n) asm volatile("s_waitcnt vmcnt(" #n ")" ::: "memory")
; #define WAIT_L(n) asm volatile("s_waitcnt lgkmcnt(" #n ")" ::: "memory")
; #define BAR __builtin_amdgcn_s_barrier()
; #define SCHED __builtin_amdgcn_sched_barrier(0)
; __device__ __forceinline__ void gemm_tile(const TileDesc& td, unsigned char* lds) {
;     ...
;     for (int t = 0; t < nt - 2; t += 2) {
;         LDB(B0, 0, 0); SCHED; LDA(At, 0, 0); STAGE(SA(1, 1), A, lda, brow + HALF, t + 1);
;         WAIT_L(8); BAR; WAIT_L(0); MMA(0, 0, At, B0); BAR; SCHED;
;         LDB(B1, 0, 1); STAGE(SB(0, 0), Bt, ldb, bcol, t + 2);
;         BAR; WAIT_L(0); MMA(0, 1, At, B1); BAR;
;         LDA(At, 0, 1); STAGE(SA(0, 0), A, lda, brow, t + 2);
;         BAR; WAIT_L(0); MMA(1, 0, At, B0); BAR; SCHED;
;         STAGE(SB(0, 1), Bt, ldb, bcol + HALF, t + 2);
;         WAIT_V(6); BAR; MMA(1, 1, At, B1); BAR;
.LBB0_247:
	ds_read_b128 v[190:193], v183
	ds_read_b128 v[194:197], v183 offset:1024
	ds_read_b128 v[198:201], v183 offset:2048
	ds_read_b128 v[202:205], v183 offset:3072
	s_add_u32 s7, s4, s78
	s_addc_u32 s62, s5, s79
	s_add_u32 s30, s7, 0x80
	v_add_u32_e32 v162, 0xc000, v139
	s_addc_u32 s31, s62, 0
	v_readfirstlane_b32 s63, v162
	v_add_u32_e32 v252, v182, v154
	v_lshl_add_u64 v[160:161], s[30:31], 0, v[128:129]
	s_mov_b32 m0, s63
	v_add_u32_e32 v162, 0xe000, v139
	ds_read_b128 v[206:209], v252
	ds_read_b128 v[210:213], v252 offset:1024
	ds_read_b128 v[214:217], v184
	ds_read_b128 v[218:221], v184 offset:1024
	ds_read_b128 v[222:225], v185
	ds_read_b128 v[226:229], v185 offset:1024
	ds_read_b128 v[230:233], v186
	ds_read_b128 v[234:237], v186 offset:1024
	global_load_lds_dwordx4 v[160:161], off
	v_lshl_add_u64 v[160:161], s[30:31], 0, v[130:131]
	v_readfirstlane_b32 s30, v162
	s_mov_b32 m0, s30
	s_nop 0
	global_load_lds_dwordx4 v[160:161], off
	s_waitcnt lgkmcnt(8)
	s_barrier
	s_waitcnt lgkmcnt(0)
	s_waitcnt lgkmcnt(0)
	v_mfma_f32_16x16x32_bf16 v[100:103], v[190:193], v[206:209], v[100:103]
	v_mfma_f32_16x16x32_bf16 v[124:127], v[198:201], v[206:209], v[124:127]
	v_mfma_f32_16x16x32_bf16 v[120:123], v[190:193], v[214:217], v[120:123]
	v_mfma_f32_16x16x32_bf16 v[116:119], v[198:201], v[214:217], v[116:119]
	v_mfma_f32_16x16x32_bf16 v[112:115], v[190:193], v[222:225], v[112:115]
	v_mfma_f32_16x16x32_bf16 v[108:111], v[198:201], v[222:225], v[108:111]
	v_mfma_f32_16x16x32_bf16 v[104:107], v[190:193], v[230:233], v[104:107]
	v_mfma_f32_16x16x32_bf16 v[96:99], v[198:201], v[230:233], v[96:99]
	v_mfma_f32_16x16x32_bf16 v[100:103], v[194:197], v[210:213], v[100:103]
	v_mfma_f32_16x16x32_bf16 v[124:127], v[202:205], v[210:213], v[124:127]
	v_mfma_f32_16x16x32_bf16 v[120:123], v[194:197], v[218:221], v[120:123]
	v_mfma_f32_16x16x32_bf16 v[116:119], v[202:205], v[218:221], v[116:119]
	v_mfma_f32_16x16x32_bf16 v[112:115], v[194:197], v[226:229], v[112:115]
	v_mfma_f32_16x16x32_bf16 v[108:111], v[202:205], v[226:229], v[108:111]
	v_mfma_f32_16x16x32_bf16 v[104:107], v[194:197], v[234:237], v[104:107]
	v_mfma_f32_16x16x32_bf16 v[96:99], v[202:205], v[234:237], v[96:99]
	s_barrier
	s_add_i32 s3, s3, 2
	s_add_u32 s63, s18, s78
	s_addc_u32 s65, s19, s79
	s_add_u32 s30, s63, 0x100
	s_addc_u32 s31, s65, 0
	v_readfirstlane_b32 s66, v152
	v_lshl_add_u64 v[168:169], s[30:31], 0, v[132:133]
	s_mov_b32 m0, s66
	ds_read_b128 v[238:241], v187
	ds_read_b128 v[242:245], v187 offset:1024
	ds_read_b128 v[246:249], v187 offset:2048
	ds_read_b128 v[160:163], v187 offset:3072
	global_load_lds_dwordx4 v[168:169], off
	v_lshl_add_u64 v[168:169], s[30:31], 0, v[136:137]
	v_readfirstlane_b32 s30, v153
	s_mov_b32 m0, s30
	s_nop 0
	global_load_lds_dwordx4 v[168:169], off
	s_barrier
	s_waitcnt lgkmcnt(0)
	s_waitcnt lgkmcnt(0)
	s_cmpk_eq_i32 s68, 0x500
	s_cbranch_scc1 .Lskip_b1_1
	v_mfma_f32_16x16x32_bf16 v[92:95], v[238:241], v[206:209], v[92:95]
	v_mfma_f32_16x16x32_bf16 v[88:91], v[246:249], v[206:209], v[88:91]
	v_mfma_f32_16x16x32_bf16 v[84:87], v[238:241], v[214:217], v[84:87]
	v_mfma_f32_16x16x32_bf16 v[80:83], v[246:249], v[214:217], v[80:83]
	v_mfma_f32_16x16x32_bf16 v[76:79], v[238:241], v[222:225], v[76:79]
	v_mfma_f32_16x16x32_bf16 v[72:75], v[246:249], v[222:225], v[72:75]
	v_mfma_f32_16x16x32_bf16 v[68:71], v[238:241], v[230:233], v[68:71]
	v_mfma_f32_16x16x32_bf16 v[64:67], v[246:249], v[230:233], v[64:67]
	v_mfma_f32_16x16x32_bf16 v[92:95], v[242:245], v[210:213], v[92:95]
	v_mfma_f32_16x16x32_bf16 v[88:91], v[160:163], v[210:213], v[88:91]
	v_mfma_f32_16x16x32_bf16 v[84:87], v[242:245], v[218:221], v[84:87]
	v_mfma_f32_16x16x32_bf16 v[80:83], v[160:163], v[218:221], v[80:83]
	v_mfma_f32_16x16x32_bf16 v[76:79], v[242:245], v[226:229], v[76:79]
	v_mfma_f32_16x16x32_bf16 v[72:75], v[160:163], v[226:229], v[72:75]
	v_mfma_f32_16x16x32_bf16 v[68:71], v[242:245], v[234:237], v[68:71]
	v_mfma_f32_16x16x32_bf16 v[64:67], v[160:163], v[234:237], v[64:67]
.Lskip_b1_1:
	s_add_u32 s66, s24, s78
	s_addc_u32 s67, s25, s79
	s_add_u32 s30, s66, 0x100
	s_addc_u32 s31, s67, 0
	v_readfirstlane_b32 s70, v139
	v_lshl_add_u64 v[168:169], s[30:31], 0, v[128:129]
	s_mov_b32 m0, s70
	s_barrier
	ds_read_b128 v[206:209], v252 offset:16384
	ds_read_b128 v[210:213], v252 offset:17408
	ds_read_b128 v[214:217], v184 offset:16384
	ds_read_b128 v[218:221], v184 offset:17408
	ds_read_b128 v[222:225], v185 offset:16384
	ds_read_b128 v[226:229], v185 offset:17408
	ds_read_b128 v[230:233], v186 offset:16384
	ds_read_b128 v[234:237], v186 offset:17408
	global_load_lds_dwordx4 v[168:169], off
	v_lshl_add_u64 v[168:169], s[30:31], 0, v[130:131]
	v_readfirstlane_b32 s30, v155
	s_mov_b32 m0, s30
	s_nop 0
	global_load_lds_dwordx4 v[168:169], off
	s_barrier
	s_waitcnt lgkmcnt(0)
	s_waitcnt lgkmcnt(0)
	v_mfma_f32_16x16x32_bf16 v[60:63], v[190:193], v[206:209], v[60:63]
	v_mfma_f32_16x16x32_bf16 v[56:59], v[198:201], v[206:209], v[56:59]
	v_mfma_f32_16x16x32_bf16 v[52:55], v[190:193], v[214:217], v[52:55]
	v_mfma_f32_16x16x32_bf16 v[48:51], v[198:201], v[214:217], v[48:51]
	v_mfma_f32_16x16x32_bf16 v[44:47], v[190:193], v[222:225], v[44:47]
	v_mfma_f32_16x16x32_bf16 v[40:43], v[198:201], v[222:225], v[40:43]
	v_mfma_f32_16x16x32_bf16 v[36:39], v[190:193], v[230:233], v[36:39]
	v_mfma_f32_16x16x32_bf16 v[32:35], v[198:201], v[230:233], v[32:35]
	v_mfma_f32_16x16x32_bf16 v[60:63], v[194:197], v[210:213], v[60:63]
	v_mfma_f32_16x16x32_bf16 v[56:59], v[202:205], v[210:213], v[56:59]
	v_mfma_f32_16x16x32_bf16 v[52:55], v[194:197], v[218:221], v[52:55]
	v_mfma_f32_16x16x32_bf16 v[48:51], v[202:205], v[218:221], v[48:51]
	v_mfma_f32_16x16x32_bf16 v[44:47], v[194:197], v[226:229], v[44:47]
	v_mfma_f32_16x16x32_bf16 v[40:43], v[202:205], v[226:229], v[40:43]
	v_mfma_f32_16x16x32_bf16 v[36:39], v[194:197], v[234:237], v[36:39]
	v_mfma_f32_16x16x32_bf16 v[32:35], v[202:205], v[234:237], v[32:35]
	s_barrier
; #define LDA(dst, b, h) _Pragma("unroll") for (int m = 0; m < 4; ++m) _Pragma("unroll") for (int k = 0; k < 2; ++k) \
;     dst[m][k] = *reinterpret_cast<const bf16x8*>((char*)SA(b, h) + lds_byte(wr * 64 + m * 16 + fr, k * 32 + fq * 8))
; #define LDB(dst, b, h) _Pragma("unroll") for (int n = 0; n < 2; ++n) _Pragma("unroll") for (int k = 0; k < 2; ++k) \
;     dst[n][k] = *reinterpret_cast<const bf16x8*>((char*)SB(b, h) + lds_byte(wc * 32 + n * 16 + fr, k * 32 + fq * 8))
; #define MMA(ai, bj, At_, Bt_) do { __builtin_amdgcn_s_setprio(1); \
;     _Pragma("unroll") for (int m = 0; m < 4; ++m) _Pragma("unroll") for (int n = 0; n < 2; ++n) _Pragma("unroll") for (int k = 0; k < 2; ++k) \
;       acc[ai][bj][m][n] = __builtin_amdgcn_mfma_f32_16x16x32_bf16(Bt_[n][k], At_[m][k], acc[ai][bj][m][n], 0, 0, 0); \
;     __builtin_amdgcn_s_setprio(0); } while (0)
; #define WAIT_V(n) asm volatile("s_waitcnt vmcnt(" #n ")" ::: "memory")
; #define WAIT_L(n) asm volatile("s_waitcnt lgkmcnt(" #n ")" ::: "memory")
; #define BAR __builtin_amdgcn_s_barrier()
; #define SCHED __builtin_amdgcn_sched_barrier(0)
; __device__ __forceinline__ void gemm_tile(const TileDesc& td, unsigned char* lds) {
;     ...
;         STAGE(SB(0, 1), Bt, ldb, bcol + HALF, t + 2);
;         WAIT_V(6); BAR; MMA(1, 1, At, B1); BAR;
;         LDB(B0, 1, 0); SCHED; LDA(At, 1, 0); STAGE(SA(0, 1), A, lda, brow + HALF, t + 2);
;         WAIT_L(8); BAR; WAIT_L(0); MMA(0, 0, At, B0); BAR; SCHED;
;         LDB(B1, 1, 1); STAGE(SB(1, 0), Bt, ldb, bcol, t + 3);
;         BAR; WAIT_L(0); MMA(0, 1, At, B1); BAR;
;         LDA(At, 1, 1); STAGE(SA(1, 0), A, lda, brow, t + 3);
;         BAR; WAIT_L(0); MMA(1, 0, At, B0); BAR; SCHED;
;         STAGE(SB(1, 1), Bt, ldb, bcol + HALF, t + 3);
	s_add_u32 s70, s80, s78
	s_addc_u32 s88, s81, s79
	s_add_u32 s30, s70, 0x100
	s_addc_u32 s31, s88, 0
	v_readfirstlane_b32 s89, v156
	v_lshl_add_u64 v[168:169], s[30:31], 0, v[132:133]
	s_mov_b32 m0, s89
	s_nop 0
	global_load_lds_dwordx4 v[168:169], off
	v_lshl_add_u64 v[168:169], s[30:31], 0, v[136:137]
	v_readfirstlane_b32 s30, v157
	s_mov_b32 m0, s30
	s_nop 0
	global_load_lds_dwordx4 v[168:169], off
	s_waitcnt vmcnt(6)
	s_barrier
	s_cmpk_eq_i32 s68, 0x500
	s_cbranch_scc1 .Lskip_b1_2
	v_mfma_f32_16x16x32_bf16 v[28:31], v[238:241], v[206:209], v[28:31]
	v_mfma_f32_16x16x32_bf16 v[24:27], v[246:249], v[206:209], v[24:27]
	v_mfma_f32_16x16x32_bf16 v[20:23], v[238:241], v[214:217], v[20:23]
	v_mfma_f32_16x16x32_bf16 v[16:19], v[246:249], v[214:217], v[16:19]
	v_mfma_f32_16x16x32_bf16 v[12:15], v[238:241], v[222:225], v[12:15]
	v_mfma_f32_16x16x32_bf16 v[8:11], v[246:249], v[222:225], v[8:11]
	v_mfma_f32_16x16x32_bf16 v[4:7], v[238:241], v[230:233], v[4:7]
	v_mfma_f32_16x16x32_bf16 v[0:3], v[246:249], v[230:233], v[0:3]
	v_mfma_f32_16x16x32_bf16 v[28:31], v[242:245], v[210:213], v[28:31]
	v_mfma_f32_16x16x32_bf16 v[24:27], v[160:163], v[210:213], v[24:27]
	v_mfma_f32_16x16x32_bf16 v[20:23], v[242:245], v[218:221], v[20:23]
	v_mfma_f32_16x16x32_bf16 v[16:19], v[160:163], v[218:221], v[16:19]
	v_mfma_f32_16x16x32_bf16 v[12:15], v[242:245], v[226:229], v[12:15]
	v_mfma_f32_16x16x32_bf16 v[8:11], v[160:163], v[226:229], v[8:11]
	v_mfma_f32_16x16x32_bf16 v[4:7], v[242:245], v[234:237], v[4:7]
	v_mfma_f32_16x16x32_bf16 v[0:3], v[160:163], v[234:237], v[0:3]
.Lskip_b1_2:
	s_barrier
	ds_read_b128 v[160:163], v188
	ds_read_b128 v[190:193], v188 offset:1024
	ds_read_b128 v[194:197], v188 offset:2048
	ds_read_b128 v[198:201], v188 offset:3072
	s_add_u32 s30, s7, 0x100
	s_addc_u32 s31, s62, 0
	v_readfirstlane_b32 s7, v174
	v_lshl_add_u64 v[168:169], s[30:31], 0, v[128:129]
	s_mov_b32 m0, s7
	v_readfirstlane_b32 s7, v175
	ds_read_b128 v[202:205], v252 offset:32768
	ds_read_b128 v[206:209], v252 offset:33792
	ds_read_b128 v[210:213], v184 offset:32768
	ds_read_b128 v[214:217], v184 offset:33792
	ds_read_b128 v[218:221], v185 offset:32768
	ds_read_b128 v[222:225], v185 offset:33792
	ds_read_b128 v[226:229], v186 offset:32768
	ds_read_b128 v[230:233], v186 offset:33792
	global_load_lds_dwordx4 v[168:169], off
	v_lshl_add_u64 v[168:169], s[30:31], 0, v[130:131]
	s_mov_b32 m0, s7
	s_nop 0
	global_load_lds_dwordx4 v[168:169], off
	s_waitcnt lgkmcnt(8)
	s_barrier
	s_waitcnt lgkmcnt(0)
	s_waitcnt lgkmcnt(0)
	v_mfma_f32_16x16x32_bf16 v[100:103], v[160:163], v[202:205], v[100:103]
	v_mfma_f32_16x16x32_bf16 v[124:127], v[194:197], v[202:205], v[124:127]
	v_mfma_f32_16x16x32_bf16 v[120:123], v[160:163], v[210:213], v[120:123]
	v_mfma_f32_16x16x32_bf16 v[116:119], v[194:197], v[210:213], v[116:119]
	v_mfma_f32_16x16x32_bf16 v[112:115], v[160:163], v[218:221], v[112:115]
	v_mfma_f32_16x16x32_bf16 v[108:111], v[194:197], v[218:221], v[108:111]
	v_mfma_f32_16x16x32_bf16 v[104:107], v[160:163], v[226:229], v[104:107]
	v_mfma_f32_16x16x32_bf16 v[96:99], v[194:197], v[226:229], v[96:99]
	v_mfma_f32_16x16x32_bf16 v[100:103], v[190:193], v[206:209], v[100:103]
	v_mfma_f32_16x16x32_bf16 v[124:127], v[198:201], v[206:209], v[124:127]
	v_mfma_f32_16x16x32_bf16 v[120:123], v[190:193], v[214:217], v[120:123]
	v_mfma_f32_16x16x32_bf16 v[116:119], v[198:201], v[214:217], v[116:119]
	v_mfma_f32_16x16x32_bf16 v[112:115], v[190:193], v[222:225], v[112:115]
	v_mfma_f32_16x16x32_bf16 v[108:111], v[198:201], v[222:225], v[108:111]
	v_mfma_f32_16x16x32_bf16 v[104:107], v[190:193], v[230:233], v[104:107]
	v_mfma_f32_16x16x32_bf16 v[96:99], v[198:201], v[230:233], v[96:99]
	s_barrier
	s_add_u32 s30, s63, 0x180
	s_addc_u32 s31, s65, 0
	v_readfirstlane_b32 s7, v176
	v_lshl_add_u64 v[168:169], s[30:31], 0, v[132:133]
	s_mov_b32 m0, s7
	v_readfirstlane_b32 s7, v177
	ds_read_b128 v[234:237], v189
	ds_read_b128 v[238:241], v189 offset:1024
	ds_read_b128 v[242:245], v189 offset:2048
	ds_read_b128 v[246:249], v189 offset:3072
	global_load_lds_dwordx4 v[168:169], off
	v_lshl_add_u64 v[168:169], s[30:31], 0, v[136:137]
	s_mov_b32 m0, s7
	s_nop 0
	global_load_lds_dwordx4 v[168:169], off
	s_barrier
	s_waitcnt lgkmcnt(0)
	s_waitcnt lgkmcnt(0)
	s_cmpk_eq_i32 s68, 0x500
	s_cbranch_scc1 .Lskip_b1_3
	v_mfma_f32_16x16x32_bf16 v[92:95], v[234:237], v[202:205], v[92:95]
	v_mfma_f32_16x16x32_bf16 v[88:91], v[242:245], v[202:205], v[88:91]
	v_mfma_f32_16x16x32_bf16 v[84:87], v[234:237], v[210:213], v[84:87]
	v_mfma_f32_16x16x32_bf16 v[80:83], v[242:245], v[210:213], v[80:83]
	v_mfma_f32_16x16x32_bf16 v[76:79], v[234:237], v[218:221], v[76:79]
	v_mfma_f32_16x16x32_bf16 v[72:75], v[242:245], v[218:221], v[72:75]
	v_mfma_f32_16x16x32_bf16 v[68:71], v[234:237], v[226:229], v[68:71]
	v_mfma_f32_16x16x32_bf16 v[64:67], v[242:245], v[226:229], v[64:67]
	v_mfma_f32_16x16x32_bf16 v[92:95], v[238:241], v[206:209], v[92:95]
	v_mfma_f32_16x16x32_bf16 v[88:91], v[246:249], v[206:209], v[88:91]
	v_mfma_f32_16x16x32_bf16 v[84:87], v[238:241], v[214:217], v[84:87]
	v_mfma_f32_16x16x32_bf16 v[80:83], v[246:249], v[214:217], v[80:83]
	v_mfma_f32_16x16x32_bf16 v[76:79], v[238:241], v[222:225], v[76:79]
	v_mfma_f32_16x16x32_bf16 v[72:75], v[246:249], v[222:225], v[72:75]
	v_mfma_f32_16x16x32_bf16 v[68:71], v[238:241], v[230:233], v[68:71]
	v_mfma_f32_16x16x32_bf16 v[64:67], v[246:249], v[230:233], v[64:67]
; #define LDA(dst, b, h) _Pragma("unroll") for (int m = 0; m < 4; ++m) _Pragma("unroll") for (int k = 0; k < 2; ++k) \
;     dst[m][k] = *reinterpret_cast<const bf16x8*>((char*)SA(b, h) + lds_byte(wr * 64 + m * 16 + fr, k * 32 + fq * 8))
; #define LDB(dst, b, h) _Pragma("unroll") for (int n = 0; n < 2; ++n) _Pragma("unroll") for (int k = 0; k < 2; ++k) \
;     dst[n][k] = *reinterpret_cast<const bf16x8*>((char*)SB(b, h) + lds_byte(wc * 32 + n * 16 + fr, k * 32 + fq * 8))
; #define MMA(ai, bj, At_, Bt_) do { __builtin_amdgcn_s_setprio(1); \
;     _Pragma("unroll") for (int m = 0; m < 4; ++m) _Pragma("unroll") for (int n = 0; n < 2; ++n) _Pragma("unroll") for (int k = 0; k < 2; ++k) \
;       acc[ai][bj][m][n] = __builtin_amdgcn_mfma_f32_16x16x32_bf16(Bt_[n][k], At_[m][k], acc[ai][bj][m][n], 0, 0, 0); \
;     __builtin_amdgcn_s_setprio(0); } while (0)
; #define WAIT_V(n) asm volatile("s_waitcnt vmcnt(" #n ")" ::: "memory")
; #define WAIT_L(n) asm volatile("s_waitcnt lgkmcnt(" #n ")" ::: "memory")
; #define BAR __builtin_amdgcn_s_barrier()
; #define SCHED __builtin_amdgcn_sched_barrier(0)
; __device__ __forceinline__ void gemm_tile(const TileDesc& td, unsigned char* lds) {
;     ...
;         LDA(At, 1, 1); STAGE(SA(1, 0), A, lda, brow, t + 3);
;         BAR; WAIT_L(0); MMA(1, 0, At, B0); BAR; SCHED;
;         STAGE(SB(1, 1), Bt, ldb, bcol + HALF, t + 3);
;         WAIT_V(6); BAR; MMA(1, 1, At, B1); BAR;
;     }
;     { LDB(B0, 0, 0); LDA(At, 0, 0); STAGE(SA(1, 1), A, lda, brow + HALF, nt - 1);
;       BAR; WAIT_L(0); MMA(0, 0, At, B0); BAR;
.Lskip_b1_3:
	s_add_u32 s30, s66, 0x180
	s_addc_u32 s31, s67, 0
	v_readfirstlane_b32 s7, v178
	v_lshl_add_u64 v[168:169], s[30:31], 0, v[128:129]
	s_mov_b32 m0, s7
	v_readfirstlane_b32 s7, v179
	s_barrier
	ds_read_b128 v[202:205], v252 offset:49152
	ds_read_b128 v[206:209], v252 offset:50176
	ds_read_b128 v[210:213], v184 offset:49152
	ds_read_b128 v[214:217], v184 offset:50176
	ds_read_b128 v[218:221], v185 offset:49152
	ds_read_b128 v[222:225], v185 offset:50176
	ds_read_b128 v[226:229], v186 offset:49152
	ds_read_b128 v[230:233], v186 offset:50176
	global_load_lds_dwordx4 v[168:169], off
	v_lshl_add_u64 v[168:169], s[30:31], 0, v[130:131]
	s_mov_b32 m0, s7
	s_nop 0
	global_load_lds_dwordx4 v[168:169], off
	s_barrier
	s_waitcnt lgkmcnt(0)
	s_waitcnt lgkmcnt(0)
	v_mfma_f32_16x16x32_bf16 v[60:63], v[160:163], v[202:205], v[60:63]
	v_mfma_f32_16x16x32_bf16 v[56:59], v[194:197], v[202:205], v[56:59]
	v_mfma_f32_16x16x32_bf16 v[52:55], v[160:163], v[210:213], v[52:55]
	v_mfma_f32_16x16x32_bf16 v[48:51], v[194:197], v[210:213], v[48:51]
	v_mfma_f32_16x16x32_bf16 v[44:47], v[160:163], v[218:221], v[44:47]
	v_mfma_f32_16x16x32_bf16 v[40:43], v[194:197], v[218:221], v[40:43]
	v_mfma_f32_16x16x32_bf16 v[36:39], v[160:163], v[226:229], v[36:39]
	v_mfma_f32_16x16x32_bf16 v[32:35], v[194:197], v[226:229], v[32:35]
	v_mfma_f32_16x16x32_bf16 v[60:63], v[190:193], v[206:209], v[60:63]
	v_mfma_f32_16x16x32_bf16 v[56:59], v[198:201], v[206:209], v[56:59]
	v_mfma_f32_16x16x32_bf16 v[52:55], v[190:193], v[214:217], v[52:55]
	v_mfma_f32_16x16x32_bf16 v[48:51], v[198:201], v[214:217], v[48:51]
	v_mfma_f32_16x16x32_bf16 v[44:47], v[190:193], v[222:225], v[44:47]
	v_mfma_f32_16x16x32_bf16 v[40:43], v[198:201], v[222:225], v[40:43]
	v_mfma_f32_16x16x32_bf16 v[36:39], v[190:193], v[230:233], v[36:39]
	v_mfma_f32_16x16x32_bf16 v[32:35], v[198:201], v[230:233], v[32:35]
	s_barrier
	s_add_u32 s30, s70, 0x180
	s_addc_u32 s31, s88, 0
	v_readfirstlane_b32 s7, v180
	v_lshl_add_u64 v[160:161], s[30:31], 0, v[132:133]
	s_mov_b32 m0, s7
	v_readfirstlane_b32 s7, v181
	global_load_lds_dwordx4 v[160:161], off
	v_lshl_add_u64 v[160:161], s[30:31], 0, v[136:137]
	s_mov_b32 m0, s7
	s_nop 0
	global_load_lds_dwordx4 v[160:161], off
	s_waitcnt vmcnt(6)
	s_barrier
	s_cmpk_eq_i32 s68, 0x500
	s_cbranch_scc1 .Lskip_b1_4
	v_mfma_f32_16x16x32_bf16 v[28:31], v[234:237], v[202:205], v[28:31]
	v_mfma_f32_16x16x32_bf16 v[24:27], v[242:245], v[202:205], v[24:27]
	v_mfma_f32_16x16x32_bf16 v[20:23], v[234:237], v[210:213], v[20:23]
	v_mfma_f32_16x16x32_bf16 v[16:19], v[242:245], v[210:213], v[16:19]
	v_mfma_f32_16x16x32_bf16 v[12:15], v[234:237], v[218:221], v[12:15]
	v_mfma_f32_16x16x32_bf16 v[8:11], v[242:245], v[218:221], v[8:11]
	v_mfma_f32_16x16x32_bf16 v[4:7], v[234:237], v[226:229], v[4:7]
	v_mfma_f32_16x16x32_bf16 v[0:3], v[242:245], v[226:229], v[0:3]
	v_mfma_f32_16x16x32_bf16 v[28:31], v[238:241], v[206:209], v[28:31]
	v_mfma_f32_16x16x32_bf16 v[24:27], v[246:249], v[206:209], v[24:27]
	v_mfma_f32_16x16x32_bf16 v[20:23], v[238:241], v[214:217], v[20:23]
	v_mfma_f32_16x16x32_bf16 v[16:19], v[246:249], v[214:217], v[16:19]
	v_mfma_f32_16x16x32_bf16 v[12:15], v[238:241], v[222:225], v[12:15]
	v_mfma_f32_16x16x32_bf16 v[8:11], v[246:249], v[222:225], v[8:11]
	v_mfma_f32_16x16x32_bf16 v[4:7], v[238:241], v[230:233], v[4:7]
	v_mfma_f32_16x16x32_bf16 v[0:3], v[246:249], v[230:233], v[0:3]
.Lskip_b1_4:
	s_add_u32 s78, s78, 0x100
	s_addc_u32 s79, s79, 0
	s_cmp_lt_i32 s3, s2
	s_barrier
	s_cbranch_scc1 .LBB0_247
	v_or_b32_e32 v182, 0x400, v138
	v_or_b32_e32 v183, 0x800, v138
	v_or_b32_e32 v184, 0xc00, v138
	v_mov_b32_e32 v185, v154
	v_mov_b32_e32 v235, v159
	v_mov_b32_e32 v236, v172
	v_mov_b32_e32 v172, v170
	v_mov_b32_e32 v170, v173
	v_mov_b32_e32 v237, v165
	v_mov_b32_e32 v165, v167
	v_mov_b32_e32 v238, v135
	v_mov_b32_e32 v135, v171
	v_mov_b32_e32 v167, 0x42000000
.LBB0_249:
	v_add_u32_e32 v132, v151, v138
	v_add_u32_e32 v136, v151, v182
	ds_read_b128 v[152:155], v132
	ds_read_b128 v[160:163], v136
	v_add_u32_e32 v132, v151, v183
	v_add_u32_e32 v136, v151, v184
	s_ashr_i32 s7, s6, 31
	ds_read_b128 v[174:177], v132
	ds_read_b128 v[178:181], v136
	v_add_u32_e32 v136, 0, v142
	s_lshl_b64 s[2:3], s[6:7], 7
	v_add_u32_e32 v169, v136, v145
	v_add_u32_e32 v230, v136, v146
	v_add_u32_e32 v136, 0, v142
	s_add_u32 s2, s4, s2
	v_add_u32_e32 v231, v136, v147
	v_add_u32_e32 v232, v136, v148
	v_add_u32_e32 v136, 0, v142
	s_addc_u32 s3, s5, s3
	v_add_u32_e32 v233, v136, v149
	v_add_u32_e32 v234, v136, v150
	s_add_u32 s2, s2, 0xffffff80
	v_add_u32_e32 v136, 0xc000, v139
	v_add_u32_e32 v132, 0, v142
	s_addc_u32 s3, s3, -1
	v_readfirstlane_b32 s4, v136
	v_add_u32_e32 v168, v132, v185
	v_lshl_add_u64 v[128:129], s[2:3], 0, v[128:129]
	s_mov_b32 m0, s4
	v_add_u32_e32 v132, v132, v144
	ds_read_b128 v[186:189], v168
	ds_read_b128 v[190:193], v132
	ds_read_b128 v[194:197], v169
	ds_read_b128 v[198:201], v230
	ds_read_b128 v[144:147], v231
	ds_read_b128 v[202:205], v232
	ds_read_b128 v[148:151], v233
	ds_read_b128 v[206:209], v234
	global_load_lds_dwordx4 v[128:129], off
	v_lshl_add_u64 v[128:129], s[2:3], 0, v[130:131]
	v_add_u32_e32 v130, 0xe000, v139
	s_nop 0
	v_readfirstlane_b32 s2, v130
	s_mov_b32 m0, s2
	s_nop 0
	global_load_lds_dwordx4 v[128:129], off
	s_barrier
; #define LDA(dst, b, h) _Pragma("unroll") for (int m = 0; m < 4; ++m) _Pragma("unroll") for (int k = 0; k < 2; ++k) \
;     dst[m][k] = *reinterpret_cast<const bf16x8*>((char*)SA(b, h) + lds_byte(wr * 64 + m * 16 + fr, k * 32 + fq * 8))
; #define LDB(dst, b, h) _Pragma("unroll") for (int n = 0; n < 2; ++n) _Pragma("unroll") for (int k = 0; k < 2; ++k) \
;     dst[n][k] = *reinterpret_cast<const bf16x8*>((char*)SB(b, h) + lds_byte(wc * 32 + n * 16 + fr, k * 32 + fq * 8))
; #define MMA(ai, bj, At_, Bt_) do { __builtin_amdgcn_s_setprio(1); \
;     _Pragma("unroll") for (int m = 0; m < 4; ++m) _Pragma("unroll") for (int n = 0; n < 2; ++n) _Pragma("unroll") for (int k = 0; k < 2; ++k) \
;       acc[ai][bj][m][n] = __builtin_amdgcn_mfma_f32_16x16x32_bf16(Bt_[n][k], At_[m][k], acc[ai][bj][m][n], 0, 0, 0); \
;     __builtin_amdgcn_s_setprio(0); } while (0)
; #define WAIT_V(n) asm volatile("s_waitcnt vmcnt(" #n ")" ::: "memory")
; #define WAIT_L(n) asm volatile("s_waitcnt lgkmcnt(" #n ")" ::: "memory")
; #define BAR __builtin_amdgcn_s_barrier()
; __device__ __forceinline__ void gemm_tile(const TileDesc& td, unsigned char* lds) {
;     ...
;     { LDB(B0, 0, 0); LDA(At, 0, 0); STAGE(SA(1, 1), A, lda, brow + HALF, nt - 1);
;       BAR; WAIT_L(0); MMA(0, 0, At, B0); BAR;
;       LDB(B1, 0, 1); BAR; WAIT_L(0); MMA(0, 1, At, B1); BAR;
;       LDA(At, 0, 1); WAIT_V(4); BAR; WAIT_L(0); MMA(1, 0, At, B0); MMA(1, 1, At, B1); BAR; }
	s_waitcnt lgkmcnt(0)
	s_waitcnt lgkmcnt(0)
	v_mfma_f32_16x16x32_bf16 v[100:103], v[152:155], v[186:189], v[100:103]
	v_mfma_f32_16x16x32_bf16 v[96:99], v[174:177], v[148:151], v[96:99]
	v_mfma_f32_16x16x32_bf16 v[100:103], v[160:163], v[190:193], v[100:103]
	v_mfma_f32_16x16x32_bf16 v[124:127], v[174:177], v[186:189], v[124:127]
	v_mfma_f32_16x16x32_bf16 v[120:123], v[152:155], v[194:197], v[120:123]
	v_mfma_f32_16x16x32_bf16 v[116:119], v[174:177], v[194:197], v[116:119]
	v_mfma_f32_16x16x32_bf16 v[112:115], v[152:155], v[144:147], v[112:115]
	v_mfma_f32_16x16x32_bf16 v[108:111], v[174:177], v[144:147], v[108:111]
	v_mfma_f32_16x16x32_bf16 v[104:107], v[152:155], v[148:151], v[104:107]
	v_mfma_f32_16x16x32_bf16 v[96:99], v[178:181], v[206:209], v[96:99]
	v_mfma_f32_16x16x32_bf16 v[128:131], v[178:181], v[190:193], v[124:127]
	v_mfma_f32_16x16x32_bf16 v[210:213], v[160:163], v[198:201], v[120:123]
	v_mfma_f32_16x16x32_bf16 v[214:217], v[178:181], v[198:201], v[116:119]
	v_mfma_f32_16x16x32_bf16 v[218:221], v[160:163], v[202:205], v[112:115]
	v_mfma_f32_16x16x32_bf16 v[222:225], v[178:181], v[202:205], v[108:111]
	v_mfma_f32_16x16x32_bf16 v[226:229], v[160:163], v[206:209], v[104:107]
	s_nop 1
	v_add_u32_e32 v104, v143, v138
	v_add_u32_e32 v108, v143, v182
	v_add_u32_e32 v112, v143, v183
	v_add_u32_e32 v116, v143, v184
	s_barrier
	ds_read_b128 v[104:107], v104
	ds_read_b128 v[108:111], v108
	ds_read_b128 v[112:115], v112
	ds_read_b128 v[116:119], v116
	s_barrier
	s_waitcnt lgkmcnt(0)
	s_waitcnt lgkmcnt(0)
	s_cmpk_eq_i32 s68, 0x500
	s_cbranch_scc1 .Lskip_b1_5
	v_mfma_f32_16x16x32_bf16 v[92:95], v[104:107], v[186:189], v[92:95]
	v_mfma_f32_16x16x32_bf16 v[88:91], v[112:115], v[186:189], v[88:91]
	v_mfma_f32_16x16x32_bf16 v[84:87], v[104:107], v[194:197], v[84:87]
	v_mfma_f32_16x16x32_bf16 v[80:83], v[112:115], v[194:197], v[80:83]
	v_mfma_f32_16x16x32_bf16 v[76:79], v[104:107], v[144:147], v[76:79]
	v_mfma_f32_16x16x32_bf16 v[72:75], v[112:115], v[144:147], v[72:75]
	v_mfma_f32_16x16x32_bf16 v[68:71], v[104:107], v[148:151], v[68:71]
	v_mfma_f32_16x16x32_bf16 v[64:67], v[112:115], v[148:151], v[64:67]
	v_mfma_f32_16x16x32_bf16 v[92:95], v[108:111], v[190:193], v[92:95]
	v_mfma_f32_16x16x32_bf16 v[88:91], v[116:119], v[190:193], v[88:91]
	v_mfma_f32_16x16x32_bf16 v[84:87], v[108:111], v[198:201], v[84:87]
	v_mfma_f32_16x16x32_bf16 v[80:83], v[116:119], v[198:201], v[80:83]
	v_mfma_f32_16x16x32_bf16 v[76:79], v[108:111], v[202:205], v[76:79]
	v_mfma_f32_16x16x32_bf16 v[72:75], v[116:119], v[202:205], v[72:75]
	v_mfma_f32_16x16x32_bf16 v[68:71], v[108:111], v[206:209], v[68:71]
	v_mfma_f32_16x16x32_bf16 v[64:67], v[116:119], v[206:209], v[64:67]
.Lskip_b1_5:
	s_barrier
	ds_read_b128 v[120:123], v168 offset:16384
	ds_read_b128 v[124:127], v132 offset:16384
	ds_read_b128 v[142:145], v169 offset:16384
	ds_read_b128 v[146:149], v230 offset:16384
	ds_read_b128 v[186:189], v231 offset:16384
	ds_read_b128 v[190:193], v232 offset:16384
	ds_read_b128 v[194:197], v233 offset:16384
	ds_read_b128 v[198:201], v234 offset:16384
	s_waitcnt vmcnt(4)
	s_barrier
	s_waitcnt lgkmcnt(0)
	s_waitcnt lgkmcnt(0)
	v_mfma_f32_16x16x32_bf16 v[60:63], v[152:155], v[120:123], v[60:63]
	v_mfma_f32_16x16x32_bf16 v[56:59], v[174:177], v[120:123], v[56:59]
	v_mfma_f32_16x16x32_bf16 v[52:55], v[152:155], v[142:145], v[52:55]
	v_mfma_f32_16x16x32_bf16 v[48:51], v[174:177], v[142:145], v[48:51]
	v_mfma_f32_16x16x32_bf16 v[44:47], v[152:155], v[186:189], v[44:47]
	v_mfma_f32_16x16x32_bf16 v[40:43], v[174:177], v[186:189], v[40:43]
	v_mfma_f32_16x16x32_bf16 v[36:39], v[152:155], v[194:197], v[36:39]
	v_mfma_f32_16x16x32_bf16 v[32:35], v[174:177], v[194:197], v[32:35]
	v_mfma_f32_16x16x32_bf16 v[60:63], v[160:163], v[124:127], v[60:63]
	v_mfma_f32_16x16x32_bf16 v[56:59], v[178:181], v[124:127], v[56:59]
	v_mfma_f32_16x16x32_bf16 v[52:55], v[160:163], v[146:149], v[52:55]
	v_mfma_f32_16x16x32_bf16 v[48:51], v[178:181], v[146:149], v[48:51]
	v_mfma_f32_16x16x32_bf16 v[44:47], v[160:163], v[190:193], v[44:47]
	v_mfma_f32_16x16x32_bf16 v[40:43], v[178:181], v[190:193], v[40:43]
	v_mfma_f32_16x16x32_bf16 v[36:39], v[160:163], v[198:201], v[36:39]
	v_mfma_f32_16x16x32_bf16 v[32:35], v[178:181], v[198:201], v[32:35]
	s_cmpk_eq_i32 s68, 0x500
	s_cbranch_scc1 .Lskip_b1_6
	v_mfma_f32_16x16x32_bf16 v[28:31], v[104:107], v[120:123], v[28:31]
	v_mfma_f32_16x16x32_bf16 v[24:27], v[112:115], v[120:123], v[24:27]
	v_mfma_f32_16x16x32_bf16 v[20:23], v[104:107], v[142:145], v[20:23]
	v_mfma_f32_16x16x32_bf16 v[16:19], v[112:115], v[142:145], v[16:19]
	v_mfma_f32_16x16x32_bf16 v[12:15], v[104:107], v[186:189], v[12:15]
	v_mfma_f32_16x16x32_bf16 v[8:11], v[112:115], v[186:189], v[8:11]
	v_mfma_f32_16x16x32_bf16 v[4:7], v[104:107], v[194:197], v[4:7]
	v_mfma_f32_16x16x32_bf16 v[0:3], v[112:115], v[194:197], v[0:3]
	v_mfma_f32_16x16x32_bf16 v[28:31], v[108:111], v[124:127], v[28:31]
	v_mfma_f32_16x16x32_bf16 v[24:27], v[116:119], v[124:127], v[24:27]
	v_mfma_f32_16x16x32_bf16 v[20:23], v[108:111], v[146:149], v[20:23]
	v_mfma_f32_16x16x32_bf16 v[16:19], v[116:119], v[146:149], v[16:19]
	v_mfma_f32_16x16x32_bf16 v[12:15], v[108:111], v[190:193], v[12:15]
	v_mfma_f32_16x16x32_bf16 v[8:11], v[116:119], v[190:193], v[8:11]
	v_mfma_f32_16x16x32_bf16 v[4:7], v[108:111], v[198:201], v[4:7]
	v_mfma_f32_16x16x32_bf16 v[0:3], v[116:119], v[198:201], v[0:3]
; #define LDA(dst, b, h) _Pragma("unroll") for (int m = 0; m < 4; ++m) _Pragma("unroll") for (int k = 0; k < 2; ++k) \
;     dst[m][k] = *reinterpret_cast<const bf16x8*>((char*)SA(b, h) + lds_byte(wr * 64 + m * 16 + fr, k * 32 + fq * 8))
; #define LDB(dst, b, h) _Pragma("unroll") for (int n = 0; n < 2; ++n) _Pragma("unroll") for (int k = 0; k < 2; ++k) \
;     dst[n][k] = *reinterpret_cast<const bf16x8*>((char*)SB(b, h) + lds_byte(wc * 32 + n * 16 + fr, k * 32 + fq * 8))
; #define MMA(ai, bj, At_, Bt_) do { __builtin_amdgcn_s_setprio(1); \
;     _Pragma("unroll") for (int m = 0; m < 4; ++m) _Pragma("unroll") for (int n = 0; n < 2; ++n) _Pragma("unroll") for (int k = 0; k < 2; ++k) \
;       acc[ai][bj][m][n] = __builtin_amdgcn_mfma_f32_16x16x32_bf16(Bt_[n][k], At_[m][k], acc[ai][bj][m][n], 0, 0, 0); \
;     __builtin_amdgcn_s_setprio(0); } while (0)
; #define WAIT_V(n) asm volatile("s_waitcnt vmcnt(" #n ")" ::: "memory")
; #define WAIT_L(n) asm volatile("s_waitcnt lgkmcnt(" #n ")" ::: "memory")
; #define BAR __builtin_amdgcn_s_barrier()
; __device__ __forceinline__ void gemm_tile(const TileDesc& td, unsigned char* lds) {
;     ...
;     { LDB(B0, 1, 0); LDA(At, 1, 0); WAIT_V(2); BAR; WAIT_L(0); MMA(0, 0, At, B0); BAR;
;       LDB(B1, 1, 1); WAIT_V(0); BAR; WAIT_L(0); MMA(0, 1, At, B1); BAR;
;       LDA(At, 1, 1); BAR; WAIT_L(0); MMA(1, 0, At, B0); MMA(1, 1, At, B1); BAR; }
;     if (wr == 0) BAR;
.Lskip_b1_6:
	v_add_u32_e32 v104, v141, v138
	s_barrier
	v_add_u32_e32 v105, v141, v182
	ds_read_b128 v[142:145], v104
	ds_read_b128 v[146:149], v105
	v_add_u32_e32 v104, v141, v183
	v_add_u32_e32 v105, v141, v184
	ds_read_b128 v[150:153], v104
	ds_read_b128 v[154:157], v105
	ds_read_b128 v[160:163], v168 offset:32768
	ds_read_b128 v[174:177], v132 offset:32768
	ds_read_b128 v[178:181], v169 offset:32768
	ds_read_b128 v[186:189], v230 offset:32768
	ds_read_b128 v[190:193], v231 offset:32768
	ds_read_b128 v[194:197], v232 offset:32768
	ds_read_b128 v[198:201], v233 offset:32768
	ds_read_b128 v[202:205], v234 offset:32768
	s_waitcnt vmcnt(2)
	s_barrier
	s_waitcnt lgkmcnt(0)
	s_waitcnt lgkmcnt(0)
	v_mfma_f32_16x16x32_bf16 v[100:103], v[142:145], v[160:163], v[100:103]
	v_mfma_f32_16x16x32_bf16 v[124:127], v[146:149], v[174:177], v[100:103]
	v_mfma_f32_16x16x32_bf16 v[100:103], v[150:153], v[160:163], v[128:131]
	v_mfma_f32_16x16x32_bf16 v[120:123], v[154:157], v[174:177], v[100:103]
	v_mfma_f32_16x16x32_bf16 v[100:103], v[142:145], v[178:181], v[210:213]
	v_mfma_f32_16x16x32_bf16 v[116:119], v[146:149], v[186:189], v[100:103]
	v_mfma_f32_16x16x32_bf16 v[100:103], v[150:153], v[178:181], v[214:217]
	v_mfma_f32_16x16x32_bf16 v[112:115], v[154:157], v[186:189], v[100:103]
	v_mfma_f32_16x16x32_bf16 v[100:103], v[142:145], v[190:193], v[218:221]
	v_mfma_f32_16x16x32_bf16 v[108:111], v[146:149], v[194:197], v[100:103]
	v_mfma_f32_16x16x32_bf16 v[100:103], v[150:153], v[190:193], v[222:225]
	v_mfma_f32_16x16x32_bf16 v[104:107], v[154:157], v[194:197], v[100:103]
	v_mfma_f32_16x16x32_bf16 v[100:103], v[142:145], v[198:201], v[226:229]
	v_mfma_f32_16x16x32_bf16 v[96:99], v[150:153], v[198:201], v[96:99]
	v_mfma_f32_16x16x32_bf16 v[100:103], v[146:149], v[202:205], v[100:103]
	v_mfma_f32_16x16x32_bf16 v[96:99], v[154:157], v[202:205], v[96:99]
	v_add_u32_e32 v128, v140, v138
	v_add_u32_e32 v136, v140, v182
	v_add_u32_e32 v141, v140, v183
	s_barrier
	ds_read_b128 v[128:131], v128
	ds_read_b128 v[136:139], v136
	v_add_u32_e32 v140, v140, v184
	ds_read_b128 v[182:185], v141
	ds_read_b128 v[206:209], v140
	s_waitcnt vmcnt(0)
	s_barrier
	s_waitcnt lgkmcnt(0)
	s_waitcnt lgkmcnt(0)
	s_cmpk_eq_i32 s68, 0x500
	s_cbranch_scc1 .Lskip_b1_7
	v_mfma_f32_16x16x32_bf16 v[92:95], v[128:131], v[160:163], v[92:95]
	v_mfma_f32_16x16x32_bf16 v[88:91], v[182:185], v[160:163], v[88:91]
	v_mfma_f32_16x16x32_bf16 v[84:87], v[128:131], v[178:181], v[84:87]
	v_mfma_f32_16x16x32_bf16 v[80:83], v[182:185], v[178:181], v[80:83]
	v_mfma_f32_16x16x32_bf16 v[76:79], v[128:131], v[190:193], v[76:79]
	v_mfma_f32_16x16x32_bf16 v[72:75], v[182:185], v[190:193], v[72:75]
	v_mfma_f32_16x16x32_bf16 v[68:71], v[128:131], v[198:201], v[68:71]
	v_mfma_f32_16x16x32_bf16 v[64:67], v[182:185], v[198:201], v[64:67]
	v_mfma_f32_16x16x32_bf16 v[92:95], v[136:139], v[174:177], v[92:95]
	v_mfma_f32_16x16x32_bf16 v[88:91], v[206:209], v[174:177], v[88:91]
	v_mfma_f32_16x16x32_bf16 v[84:87], v[136:139], v[186:189], v[84:87]
	v_mfma_f32_16x16x32_bf16 v[80:83], v[206:209], v[186:189], v[80:83]
	v_mfma_f32_16x16x32_bf16 v[76:79], v[136:139], v[194:197], v[76:79]
	v_mfma_f32_16x16x32_bf16 v[72:75], v[206:209], v[194:197], v[72:75]
	v_mfma_f32_16x16x32_bf16 v[68:71], v[136:139], v[202:205], v[68:71]
	v_mfma_f32_16x16x32_bf16 v[64:67], v[206:209], v[202:205], v[64:67]
.Lskip_b1_7:
	s_barrier
	ds_read_b128 v[160:163], v168 offset:49152
	ds_read_b128 v[174:177], v132 offset:49152
	ds_read_b128 v[178:181], v169 offset:49152
	ds_read_b128 v[186:189], v230 offset:49152
	ds_read_b128 v[190:193], v231 offset:49152
	ds_read_b128 v[194:197], v232 offset:49152
	ds_read_b128 v[198:201], v233 offset:49152
	ds_read_b128 v[202:205], v234 offset:49152
	s_barrier
	s_waitcnt lgkmcnt(0)
	s_waitcnt lgkmcnt(0)
	v_mfma_f32_16x16x32_bf16 v[60:63], v[142:145], v[160:163], v[60:63]
	v_mfma_f32_16x16x32_bf16 v[56:59], v[150:153], v[160:163], v[56:59]
	v_mfma_f32_16x16x32_bf16 v[52:55], v[142:145], v[178:181], v[52:55]
	v_mfma_f32_16x16x32_bf16 v[48:51], v[150:153], v[178:181], v[48:51]
	v_mfma_f32_16x16x32_bf16 v[44:47], v[142:145], v[190:193], v[44:47]
	v_mfma_f32_16x16x32_bf16 v[40:43], v[150:153], v[190:193], v[40:43]
	v_mfma_f32_16x16x32_bf16 v[36:39], v[142:145], v[198:201], v[36:39]
	v_mfma_f32_16x16x32_bf16 v[32:35], v[150:153], v[198:201], v[32:35]
	v_mfma_f32_16x16x32_bf16 v[60:63], v[146:149], v[174:177], v[60:63]
	v_mfma_f32_16x16x32_bf16 v[56:59], v[154:157], v[174:177], v[56:59]
	v_mfma_f32_16x16x32_bf16 v[52:55], v[146:149], v[186:189], v[52:55]
	v_mfma_f32_16x16x32_bf16 v[48:51], v[154:157], v[186:189], v[48:51]
	v_mfma_f32_16x16x32_bf16 v[44:47], v[146:149], v[194:197], v[44:47]
	v_mfma_f32_16x16x32_bf16 v[40:43], v[154:157], v[194:197], v[40:43]
	v_mfma_f32_16x16x32_bf16 v[36:39], v[146:149], v[202:205], v[36:39]
	v_mfma_f32_16x16x32_bf16 v[32:35], v[154:157], v[202:205], v[32:35]
	s_cmpk_eq_i32 s68, 0x500
	s_cbranch_scc1 .Lskip_b1_8
	v_mfma_f32_16x16x32_bf16 v[28:31], v[128:131], v[160:163], v[28:31]
	v_mfma_f32_16x16x32_bf16 v[24:27], v[182:185], v[160:163], v[24:27]
	v_mfma_f32_16x16x32_bf16 v[20:23], v[128:131], v[178:181], v[20:23]
	v_mfma_f32_16x16x32_bf16 v[16:19], v[182:185], v[178:181], v[16:19]
	v_mfma_f32_16x16x32_bf16 v[12:15], v[128:131], v[190:193], v[12:15]
	v_mfma_f32_16x16x32_bf16 v[8:11], v[182:185], v[190:193], v[8:11]
	v_mfma_f32_16x16x32_bf16 v[4:7], v[128:131], v[198:201], v[4:7]
	v_mfma_f32_16x16x32_bf16 v[0:3], v[182:185], v[198:201], v[0:3]
	v_mfma_f32_16x16x32_bf16 v[28:31], v[136:139], v[174:177], v[28:31]
	v_mfma_f32_16x16x32_bf16 v[24:27], v[206:209], v[174:177], v[24:27]
	v_mfma_f32_16x16x32_bf16 v[20:23], v[136:139], v[186:189], v[20:23]
	v_mfma_f32_16x16x32_bf16 v[16:19], v[206:209], v[186:189], v[16:19]
	v_mfma_f32_16x16x32_bf16 v[12:15], v[136:139], v[194:197], v[12:15]
	v_mfma_f32_16x16x32_bf16 v[8:11], v[206:209], v[194:197], v[8:11]
	v_mfma_f32_16x16x32_bf16 v[4:7], v[136:139], v[202:205], v[4:7]
	v_mfma_f32_16x16x32_bf16 v[0:3], v[206:209], v[202:205], v[0:3]
.Lskip_b1_8:
	s_movk_i32 s2, 0x100
	v_cmp_gt_u32_e32 vcc, s2, v134
	s_barrier
	s_and_saveexec_b64 s[4:5], vcc
	s_cbranch_execz .LBB0_251
	s_barrier
